# RG-LRU carry pass: chunk loads double-buffered in groups of 8 with counted waits
# speedup vs baseline: 1.0068x; 1.0068x over previous
; DI int tid_fresh() { int t = threadIdx.x; asm volatile("" : "+v"(t)); return t; }
; DI void phase_scan_carry(const float* asum, float* hend) {
;   for (int it = blockIdx.x * 512 + tid_fresh(); it < NB * DM; it += gridDim.x * 512) {
;     const int ch = it & (DM - 1), b = it >> 11;
;     float H = 0.f;
;     for (int c0 = 0; c0 < 128; c0 += 16) {
;       float a[16], he[16];
; #pragma unroll
;       for (int i = 0; i < 16; ++i) { const size_t o = ((size_t)b * 128 + c0 + i) * DM + ch; a[i] = asum[o]; he[i] = hend[o]; }
; #pragma unroll
;       for (int i = 0; i < 16; ++i) { const size_t o = ((size_t)b * 128 + c0 + i) * DM + ch; hend[o] = H; H = __expf(a[i]) * H + he[i]; }
;     }
;   }
; }
.LBB0_45:
	v_mov_b32_e32 v4, 0xffbe2000
	v_mov_b32_e32 v5, -1
	v_lshl_add_u64 v[6:7], v[2:3], 0, v[4:5]
	v_mov_b32_e32 v4, 0xfffe2000
	v_lshl_add_u64 v[8:9], v[2:3], 0, v[4:5]
	v_mov_b32_e32 v10, v8
	v_mov_b32_e32 v11, v9
	v_mov_b32_e32 v4, 0x2000
	v_mov_b32_e32 v5, 0
	global_load_dword v40, v[6:7], off
	global_load_dword v48, v[8:9], off
	v_lshl_add_u64 v[6:7], v[6:7], 0, v[4:5]
	v_lshl_add_u64 v[8:9], v[8:9], 0, v[4:5]
	global_load_dword v41, v[6:7], off
	global_load_dword v49, v[8:9], off
	v_lshl_add_u64 v[6:7], v[6:7], 0, v[4:5]
	v_lshl_add_u64 v[8:9], v[8:9], 0, v[4:5]
	global_load_dword v42, v[6:7], off
	global_load_dword v50, v[8:9], off
	v_lshl_add_u64 v[6:7], v[6:7], 0, v[4:5]
	v_lshl_add_u64 v[8:9], v[8:9], 0, v[4:5]
	global_load_dword v43, v[6:7], off
	global_load_dword v51, v[8:9], off
	v_lshl_add_u64 v[6:7], v[6:7], 0, v[4:5]
	v_lshl_add_u64 v[8:9], v[8:9], 0, v[4:5]
	global_load_dword v44, v[6:7], off
	global_load_dword v52, v[8:9], off
	v_lshl_add_u64 v[6:7], v[6:7], 0, v[4:5]
	v_lshl_add_u64 v[8:9], v[8:9], 0, v[4:5]
	global_load_dword v45, v[6:7], off
	global_load_dword v53, v[8:9], off
	v_lshl_add_u64 v[6:7], v[6:7], 0, v[4:5]
	v_lshl_add_u64 v[8:9], v[8:9], 0, v[4:5]
	global_load_dword v46, v[6:7], off
	global_load_dword v54, v[8:9], off
	v_lshl_add_u64 v[6:7], v[6:7], 0, v[4:5]
	v_lshl_add_u64 v[8:9], v[8:9], 0, v[4:5]
	global_load_dword v47, v[6:7], off
	global_load_dword v55, v[8:9], off
	v_lshl_add_u64 v[6:7], v[6:7], 0, v[4:5]
	v_lshl_add_u64 v[8:9], v[8:9], 0, v[4:5]
	global_load_dword v56, v[6:7], off
	global_load_dword v64, v[8:9], off
	v_lshl_add_u64 v[6:7], v[6:7], 0, v[4:5]
	v_lshl_add_u64 v[8:9], v[8:9], 0, v[4:5]
	global_load_dword v57, v[6:7], off
	global_load_dword v65, v[8:9], off
	v_lshl_add_u64 v[6:7], v[6:7], 0, v[4:5]
	v_lshl_add_u64 v[8:9], v[8:9], 0, v[4:5]
	global_load_dword v58, v[6:7], off
	global_load_dword v66, v[8:9], off
	v_lshl_add_u64 v[6:7], v[6:7], 0, v[4:5]
	v_lshl_add_u64 v[8:9], v[8:9], 0, v[4:5]
	global_load_dword v59, v[6:7], off
	global_load_dword v67, v[8:9], off
	v_lshl_add_u64 v[6:7], v[6:7], 0, v[4:5]
	v_lshl_add_u64 v[8:9], v[8:9], 0, v[4:5]
	global_load_dword v60, v[6:7], off
	global_load_dword v68, v[8:9], off
	v_lshl_add_u64 v[6:7], v[6:7], 0, v[4:5]
	v_lshl_add_u64 v[8:9], v[8:9], 0, v[4:5]
	global_load_dword v61, v[6:7], off
	global_load_dword v69, v[8:9], off
	v_lshl_add_u64 v[6:7], v[6:7], 0, v[4:5]
	v_lshl_add_u64 v[8:9], v[8:9], 0, v[4:5]
	global_load_dword v62, v[6:7], off
	global_load_dword v70, v[8:9], off
	v_lshl_add_u64 v[6:7], v[6:7], 0, v[4:5]
	v_lshl_add_u64 v[8:9], v[8:9], 0, v[4:5]
	global_load_dword v63, v[6:7], off
	global_load_dword v71, v[8:9], off
	v_lshl_add_u64 v[6:7], v[6:7], 0, v[4:5]
	v_lshl_add_u64 v[8:9], v[8:9], 0, v[4:5]
	s_mov_b32 s14, 0
.Lcarry_loop:
	s_waitcnt vmcnt(22)
	v_mul_f32_e32 v31, 0x3fb8aa3b, v40
	v_exp_f32_e32 v31, v31
	global_store_dword v[10:11], v29, off
	v_lshl_add_u64 v[10:11], v[10:11], 0, v[4:5]
	v_fma_f32 v30, v29, v31, v48
	s_waitcnt vmcnt(21)
	v_mul_f32_e32 v31, 0x3fb8aa3b, v41
	v_exp_f32_e32 v31, v31
	global_store_dword v[10:11], v30, off
	v_lshl_add_u64 v[10:11], v[10:11], 0, v[4:5]
	v_fma_f32 v29, v30, v31, v49
	s_waitcnt vmcnt(20)
	v_mul_f32_e32 v31, 0x3fb8aa3b, v42
	v_exp_f32_e32 v31, v31
	global_store_dword v[10:11], v29, off
	v_lshl_add_u64 v[10:11], v[10:11], 0, v[4:5]
	v_fma_f32 v30, v29, v31, v50
	s_waitcnt vmcnt(19)
	v_mul_f32_e32 v31, 0x3fb8aa3b, v43
	v_exp_f32_e32 v31, v31
	global_store_dword v[10:11], v30, off
	v_lshl_add_u64 v[10:11], v[10:11], 0, v[4:5]
	v_fma_f32 v29, v30, v31, v51
	s_waitcnt vmcnt(18)
	v_mul_f32_e32 v31, 0x3fb8aa3b, v44
	v_exp_f32_e32 v31, v31
	global_store_dword v[10:11], v29, off
	v_lshl_add_u64 v[10:11], v[10:11], 0, v[4:5]
	v_fma_f32 v30, v29, v31, v52
	s_waitcnt vmcnt(17)
	v_mul_f32_e32 v31, 0x3fb8aa3b, v45
	v_exp_f32_e32 v31, v31
	global_store_dword v[10:11], v30, off
	v_lshl_add_u64 v[10:11], v[10:11], 0, v[4:5]
	v_fma_f32 v29, v30, v31, v53
	s_waitcnt vmcnt(16)
	v_mul_f32_e32 v31, 0x3fb8aa3b, v46
	v_exp_f32_e32 v31, v31
	global_store_dword v[10:11], v29, off
	v_lshl_add_u64 v[10:11], v[10:11], 0, v[4:5]
	v_fma_f32 v30, v29, v31, v54
	s_waitcnt vmcnt(15)
	v_mul_f32_e32 v31, 0x3fb8aa3b, v47
	v_exp_f32_e32 v31, v31
	global_store_dword v[10:11], v30, off
	v_lshl_add_u64 v[10:11], v[10:11], 0, v[4:5]
	v_fma_f32 v29, v30, v31, v55
	s_cmp_ge_u32 s14, 7
	s_cbranch_scc1 .Lcarry_na
	global_load_dword v40, v[6:7], off
	global_load_dword v48, v[8:9], off
	v_lshl_add_u64 v[6:7], v[6:7], 0, v[4:5]
	v_lshl_add_u64 v[8:9], v[8:9], 0, v[4:5]
	global_load_dword v41, v[6:7], off
	global_load_dword v49, v[8:9], off
	v_lshl_add_u64 v[6:7], v[6:7], 0, v[4:5]
	v_lshl_add_u64 v[8:9], v[8:9], 0, v[4:5]
	global_load_dword v42, v[6:7], off
	global_load_dword v50, v[8:9], off
	v_lshl_add_u64 v[6:7], v[6:7], 0, v[4:5]
	v_lshl_add_u64 v[8:9], v[8:9], 0, v[4:5]
	global_load_dword v43, v[6:7], off
	global_load_dword v51, v[8:9], off
	v_lshl_add_u64 v[6:7], v[6:7], 0, v[4:5]
	v_lshl_add_u64 v[8:9], v[8:9], 0, v[4:5]
	global_load_dword v44, v[6:7], off
	global_load_dword v52, v[8:9], off
	v_lshl_add_u64 v[6:7], v[6:7], 0, v[4:5]
	v_lshl_add_u64 v[8:9], v[8:9], 0, v[4:5]
	global_load_dword v45, v[6:7], off
	global_load_dword v53, v[8:9], off
	v_lshl_add_u64 v[6:7], v[6:7], 0, v[4:5]
	v_lshl_add_u64 v[8:9], v[8:9], 0, v[4:5]
	global_load_dword v46, v[6:7], off
	global_load_dword v54, v[8:9], off
	v_lshl_add_u64 v[6:7], v[6:7], 0, v[4:5]
	v_lshl_add_u64 v[8:9], v[8:9], 0, v[4:5]
	global_load_dword v47, v[6:7], off
	global_load_dword v55, v[8:9], off
	v_lshl_add_u64 v[6:7], v[6:7], 0, v[4:5]
	v_lshl_add_u64 v[8:9], v[8:9], 0, v[4:5]
; DI int tid_fresh() { int t = threadIdx.x; asm volatile("" : "+v"(t)); return t; }
; DI void phase_scan_carry(const float* asum, float* hend) {
;   for (int it = blockIdx.x * 512 + tid_fresh(); it < NB * DM; it += gridDim.x * 512) {
;     const int ch = it & (DM - 1), b = it >> 11;
;     float H = 0.f;
;     for (int c0 = 0; c0 < 128; c0 += 16) {
;       float a[16], he[16];
; #pragma unroll
;       for (int i = 0; i < 16; ++i) { const size_t o = ((size_t)b * 128 + c0 + i) * DM + ch; a[i] = asum[o]; he[i] = hend[o]; }
; #pragma unroll
;       for (int i = 0; i < 16; ++i) { const size_t o = ((size_t)b * 128 + c0 + i) * DM + ch; hend[o] = H; H = __expf(a[i]) * H + he[i]; }
;     }
;   }
; }
.Lcarry_na:
	s_waitcnt vmcnt(22)
	v_mul_f32_e32 v31, 0x3fb8aa3b, v56
	v_exp_f32_e32 v31, v31
	global_store_dword v[10:11], v29, off
	v_lshl_add_u64 v[10:11], v[10:11], 0, v[4:5]
	v_fma_f32 v30, v29, v31, v64
	s_waitcnt vmcnt(21)
	v_mul_f32_e32 v31, 0x3fb8aa3b, v57
	v_exp_f32_e32 v31, v31
	global_store_dword v[10:11], v30, off
	v_lshl_add_u64 v[10:11], v[10:11], 0, v[4:5]
	v_fma_f32 v29, v30, v31, v65
	s_waitcnt vmcnt(20)
	v_mul_f32_e32 v31, 0x3fb8aa3b, v58
	v_exp_f32_e32 v31, v31
	global_store_dword v[10:11], v29, off
	v_lshl_add_u64 v[10:11], v[10:11], 0, v[4:5]
	v_fma_f32 v30, v29, v31, v66
	s_waitcnt vmcnt(19)
	v_mul_f32_e32 v31, 0x3fb8aa3b, v59
	v_exp_f32_e32 v31, v31
	global_store_dword v[10:11], v30, off
	v_lshl_add_u64 v[10:11], v[10:11], 0, v[4:5]
	v_fma_f32 v29, v30, v31, v67
	s_waitcnt vmcnt(18)
	v_mul_f32_e32 v31, 0x3fb8aa3b, v60
	v_exp_f32_e32 v31, v31
	global_store_dword v[10:11], v29, off
	v_lshl_add_u64 v[10:11], v[10:11], 0, v[4:5]
	v_fma_f32 v30, v29, v31, v68
	s_waitcnt vmcnt(17)
	v_mul_f32_e32 v31, 0x3fb8aa3b, v61
	v_exp_f32_e32 v31, v31
	global_store_dword v[10:11], v30, off
	v_lshl_add_u64 v[10:11], v[10:11], 0, v[4:5]
	v_fma_f32 v29, v30, v31, v69
	s_waitcnt vmcnt(16)
	v_mul_f32_e32 v31, 0x3fb8aa3b, v62
	v_exp_f32_e32 v31, v31
	global_store_dword v[10:11], v29, off
	v_lshl_add_u64 v[10:11], v[10:11], 0, v[4:5]
	v_fma_f32 v30, v29, v31, v70
	s_waitcnt vmcnt(15)
	v_mul_f32_e32 v31, 0x3fb8aa3b, v63
	v_exp_f32_e32 v31, v31
	global_store_dword v[10:11], v30, off
	v_lshl_add_u64 v[10:11], v[10:11], 0, v[4:5]
	v_fma_f32 v29, v30, v31, v71
	s_cmp_ge_u32 s14, 7
	s_cbranch_scc1 .Lcarry_nb
	global_load_dword v56, v[6:7], off
	global_load_dword v64, v[8:9], off
	v_lshl_add_u64 v[6:7], v[6:7], 0, v[4:5]
	v_lshl_add_u64 v[8:9], v[8:9], 0, v[4:5]
	global_load_dword v57, v[6:7], off
	global_load_dword v65, v[8:9], off
	v_lshl_add_u64 v[6:7], v[6:7], 0, v[4:5]
	v_lshl_add_u64 v[8:9], v[8:9], 0, v[4:5]
	global_load_dword v58, v[6:7], off
	global_load_dword v66, v[8:9], off
	v_lshl_add_u64 v[6:7], v[6:7], 0, v[4:5]
	v_lshl_add_u64 v[8:9], v[8:9], 0, v[4:5]
	global_load_dword v59, v[6:7], off
	global_load_dword v67, v[8:9], off
	v_lshl_add_u64 v[6:7], v[6:7], 0, v[4:5]
	v_lshl_add_u64 v[8:9], v[8:9], 0, v[4:5]
	global_load_dword v60, v[6:7], off
	global_load_dword v68, v[8:9], off
	v_lshl_add_u64 v[6:7], v[6:7], 0, v[4:5]
	v_lshl_add_u64 v[8:9], v[8:9], 0, v[4:5]
	global_load_dword v61, v[6:7], off
	global_load_dword v69, v[8:9], off
	v_lshl_add_u64 v[6:7], v[6:7], 0, v[4:5]
	v_lshl_add_u64 v[8:9], v[8:9], 0, v[4:5]
	global_load_dword v62, v[6:7], off
	global_load_dword v70, v[8:9], off
	v_lshl_add_u64 v[6:7], v[6:7], 0, v[4:5]
	v_lshl_add_u64 v[8:9], v[8:9], 0, v[4:5]
	global_load_dword v63, v[6:7], off
	global_load_dword v71, v[8:9], off
	v_lshl_add_u64 v[6:7], v[6:7], 0, v[4:5]
	v_lshl_add_u64 v[8:9], v[8:9], 0, v[4:5]
.Lcarry_nb:
	s_add_i32 s14, s14, 1
	s_cmp_lt_u32 s14, 8
	s_cbranch_scc1 .Lcarry_loop
	v_add_u32_e32 v0, s3, v0
	s_movk_i32 s14, 0x1fff
	v_cmp_lt_i32_e32 vcc, s14, v0
	s_or_b64 s[12:13], vcc, s[12:13]
	v_add_u16_e32 v28, s3, v28
	s_andn2_b64 exec, exec, s[12:13]
	s_cbranch_execnz .LBB0_44
